# FFN-in K-loop LDS-DMA loads use scalar base + 32-bit per-lane offset (no per-load 64-bit VALU address adds); blocked hidden layout
# speedup vs baseline: 1.0120x; 1.0120x over previous
.LBB0_158:
	s_add_u32 s28, s30, 0xfffc0080
	s_addc_u32 s29, s31, -1
	s_cmp_eq_u32 s54, 12
	s_cselect_b32 s35, s23, s29
	s_cselect_b32 s34, s33, s28
	s_cselect_b32 s29, s21, s46
	s_cselect_b32 s28, s44, s45
	s_add_i32 s55, 0, 0x14000
	v_add_u32_e32 v142, s62, v167
	v_add_u32_e32 v171, s55, v167
	ds_read_b128 v[126:129], v142
	ds_read_b128 v[134:137], v142 offset:1024
	ds_read_b128 v[138:141], v142 offset:2048
	ds_read_b128 v[142:145], v142 offset:3072
	ds_read_b128 v[146:149], v171
	ds_read_b128 v[150:153], v171 offset:1024
	ds_read_b128 v[172:175], v171 offset:2048
	ds_read_b128 v[176:179], v171 offset:3072
	s_add_i32 m0, s41, 0xc000
	ds_read_b128 v[180:183], v170
	ds_read_b128 v[184:187], v170 offset:1024
	ds_read_b128 v[198:201], v170 offset:2048
	ds_read_b128 v[202:205], v170 offset:3072
	ds_read_b128 v[206:209], v170 offset:4096
	ds_read_b128 v[210:213], v170 offset:5120
	ds_read_b128 v[214:217], v170 offset:6144
	ds_read_b128 v[218:221], v170 offset:7168
	global_load_lds_dwordx4 v162, s[30:31]
	s_add_i32 m0, s41, 0xe000
	s_nop 0
	global_load_lds_dwordx4 v164, s[30:31]
	s_waitcnt vmcnt(8)
	s_waitcnt lgkmcnt(0)
	s_barrier
	s_setprio 1
	s_waitcnt lgkmcnt(0)
	v_mfma_f32_16x16x32_bf16 v[122:125], v[126:129], v[180:183], v[122:125]
	v_mfma_f32_16x16x32_bf16 v[114:117], v[138:141], v[180:183], v[114:117]
	v_mfma_f32_16x16x32_bf16 v[106:109], v[126:129], v[198:201], v[106:109]
	v_mfma_f32_16x16x32_bf16 v[98:101], v[138:141], v[198:201], v[98:101]
	v_mfma_f32_16x16x32_bf16 v[90:93], v[126:129], v[206:209], v[90:93]
	v_mfma_f32_16x16x32_bf16 v[82:85], v[138:141], v[206:209], v[82:85]
	v_mfma_f32_16x16x32_bf16 v[74:77], v[126:129], v[214:217], v[74:77]
	v_mfma_f32_16x16x32_bf16 v[66:69], v[138:141], v[214:217], v[66:69]
	v_mfma_f32_16x16x32_bf16 v[122:125], v[134:137], v[184:187], v[122:125]
	v_mfma_f32_16x16x32_bf16 v[114:117], v[142:145], v[184:187], v[114:117]
	v_mfma_f32_16x16x32_bf16 v[106:109], v[134:137], v[202:205], v[106:109]
	v_mfma_f32_16x16x32_bf16 v[98:101], v[142:145], v[202:205], v[98:101]
	v_mfma_f32_16x16x32_bf16 v[90:93], v[134:137], v[210:213], v[90:93]
	v_mfma_f32_16x16x32_bf16 v[82:85], v[142:145], v[210:213], v[82:85]
	v_mfma_f32_16x16x32_bf16 v[74:77], v[134:137], v[218:221], v[74:77]
	v_mfma_f32_16x16x32_bf16 v[66:69], v[142:145], v[218:221], v[66:69]
	s_setprio 0
	s_setprio 1
	v_mfma_f32_16x16x32_bf16 v[130:133], v[146:149], v[180:183], v[130:133]
	v_mfma_f32_16x16x32_bf16 v[118:121], v[172:175], v[180:183], v[118:121]
	v_mfma_f32_16x16x32_bf16 v[110:113], v[146:149], v[198:201], v[110:113]
	v_mfma_f32_16x16x32_bf16 v[102:105], v[172:175], v[198:201], v[102:105]
	v_mfma_f32_16x16x32_bf16 v[94:97], v[146:149], v[206:209], v[94:97]
	v_mfma_f32_16x16x32_bf16 v[86:89], v[172:175], v[206:209], v[86:89]
	v_mfma_f32_16x16x32_bf16 v[78:81], v[146:149], v[214:217], v[78:81]
	v_mfma_f32_16x16x32_bf16 v[70:73], v[172:175], v[214:217], v[70:73]
	v_mfma_f32_16x16x32_bf16 v[130:133], v[150:153], v[184:187], v[130:133]
	v_mfma_f32_16x16x32_bf16 v[118:121], v[176:179], v[184:187], v[118:121]
	v_mfma_f32_16x16x32_bf16 v[110:113], v[150:153], v[202:205], v[110:113]
	v_mfma_f32_16x16x32_bf16 v[102:105], v[176:179], v[202:205], v[102:105]
	v_mfma_f32_16x16x32_bf16 v[94:97], v[150:153], v[210:213], v[94:97]
	v_mfma_f32_16x16x32_bf16 v[86:89], v[176:179], v[210:213], v[86:89]
	v_mfma_f32_16x16x32_bf16 v[78:81], v[150:153], v[218:221], v[78:81]
	v_mfma_f32_16x16x32_bf16 v[70:73], v[176:179], v[218:221], v[70:73]
	s_setprio 0
	s_barrier
	s_add_i32 s56, s62, s36
	s_mov_b32 m0, s56
	ds_read_b128 v[180:183], v170 offset:16384
	ds_read_b128 v[184:187], v170 offset:17408
	ds_read_b128 v[198:201], v170 offset:18432
	ds_read_b128 v[202:205], v170 offset:19456
	ds_read_b128 v[206:209], v170 offset:20480
	ds_read_b128 v[210:213], v170 offset:21504
	ds_read_b128 v[214:217], v170 offset:22528
	ds_read_b128 v[218:221], v170 offset:23552
	global_load_lds_dwordx4 v48, s[28:29]
	s_add_i32 m0, s56, 0x2000
	s_add_u32 s68, s28, 0x40000
	s_addc_u32 s69, s29, 0
	s_add_i32 s55, s55, s36
	global_load_lds_dwordx4 v158, s[28:29]
	s_mov_b32 m0, s55
	s_nop 0
	global_load_lds_dwordx4 v48, s[68:69]
	s_add_i32 m0, s55, 0x2000
	s_nop 0
	global_load_lds_dwordx4 v158, s[68:69]
	s_mov_b32 m0, s41
	s_nop 0
	global_load_lds_dwordx4 v154, s[34:35]
	s_mov_b32 m0, s48
	s_nop 0
	global_load_lds_dwordx4 v156, s[34:35]
	s_waitcnt vmcnt(8)
	s_waitcnt lgkmcnt(0)
	s_barrier
	s_setprio 1
	s_waitcnt lgkmcnt(0)
	v_mfma_f32_16x16x32_bf16 v[58:61], v[126:129], v[180:183], v[58:61]
	v_mfma_f32_16x16x32_bf16 v[50:53], v[138:141], v[180:183], v[50:53]
	v_mfma_f32_16x16x32_bf16 v[40:43], v[126:129], v[198:201], v[40:43]
	v_mfma_f32_16x16x32_bf16 v[32:35], v[138:141], v[198:201], v[32:35]
	v_mfma_f32_16x16x32_bf16 v[24:27], v[126:129], v[206:209], v[24:27]
	v_mfma_f32_16x16x32_bf16 v[16:19], v[138:141], v[206:209], v[16:19]
	v_mfma_f32_16x16x32_bf16 v[8:11], v[126:129], v[214:217], v[8:11]
	v_mfma_f32_16x16x32_bf16 v[0:3], v[138:141], v[214:217], v[0:3]
	v_mfma_f32_16x16x32_bf16 v[58:61], v[134:137], v[184:187], v[58:61]
	v_mfma_f32_16x16x32_bf16 v[50:53], v[142:145], v[184:187], v[50:53]
	v_mfma_f32_16x16x32_bf16 v[40:43], v[134:137], v[202:205], v[40:43]
	v_mfma_f32_16x16x32_bf16 v[32:35], v[142:145], v[202:205], v[32:35]
	v_mfma_f32_16x16x32_bf16 v[24:27], v[134:137], v[210:213], v[24:27]
	v_mfma_f32_16x16x32_bf16 v[16:19], v[142:145], v[210:213], v[16:19]
	v_mfma_f32_16x16x32_bf16 v[8:11], v[134:137], v[218:221], v[8:11]
	v_mfma_f32_16x16x32_bf16 v[0:3], v[142:145], v[218:221], v[0:3]
	s_setprio 0
	s_setprio 1
	v_mfma_f32_16x16x32_bf16 v[62:65], v[146:149], v[180:183], v[62:65]
	v_mfma_f32_16x16x32_bf16 v[54:57], v[172:175], v[180:183], v[54:57]
	v_mfma_f32_16x16x32_bf16 v[44:47], v[146:149], v[198:201], v[44:47]
	v_mfma_f32_16x16x32_bf16 v[36:39], v[172:175], v[198:201], v[36:39]
	v_mfma_f32_16x16x32_bf16 v[28:31], v[146:149], v[206:209], v[28:31]
	v_mfma_f32_16x16x32_bf16 v[20:23], v[172:175], v[206:209], v[20:23]
	v_mfma_f32_16x16x32_bf16 v[12:15], v[146:149], v[214:217], v[12:15]
	v_mfma_f32_16x16x32_bf16 v[4:7], v[172:175], v[214:217], v[4:7]
	v_mfma_f32_16x16x32_bf16 v[62:65], v[150:153], v[184:187], v[62:65]
	v_mfma_f32_16x16x32_bf16 v[54:57], v[176:179], v[184:187], v[54:57]
	v_mfma_f32_16x16x32_bf16 v[44:47], v[150:153], v[202:205], v[44:47]
	v_mfma_f32_16x16x32_bf16 v[36:39], v[176:179], v[202:205], v[36:39]
	v_mfma_f32_16x16x32_bf16 v[28:31], v[150:153], v[210:213], v[28:31]
	v_mfma_f32_16x16x32_bf16 v[20:23], v[176:179], v[210:213], v[20:23]
	v_mfma_f32_16x16x32_bf16 v[12:15], v[150:153], v[218:221], v[12:15]
	v_mfma_f32_16x16x32_bf16 v[4:7], v[176:179], v[218:221], v[4:7]
	s_setprio 0
	s_barrier
	s_add_i32 s55, 0, 0x18000
	s_add_i32 s56, 0, 0x1c000
	v_add_u32_e32 v142, s55, v167
	v_add_u32_e32 v171, s56, v167
	ds_read_b128 v[126:129], v142
	ds_read_b128 v[134:137], v142 offset:1024
	ds_read_b128 v[138:141], v142 offset:2048
	ds_read_b128 v[142:145], v142 offset:3072
	ds_read_b128 v[146:149], v171
	ds_read_b128 v[150:153], v171 offset:1024
	ds_read_b128 v[172:175], v171 offset:2048
	ds_read_b128 v[176:179], v171 offset:3072
	s_add_u32 s34, s34, 0x40000
	s_addc_u32 s35, s35, 0
	s_mov_b32 m0, s49
	ds_read_b128 v[180:183], v170 offset:32768
	ds_read_b128 v[184:187], v170 offset:33792
	ds_read_b128 v[198:201], v170 offset:34816
	ds_read_b128 v[202:205], v170 offset:35840
	ds_read_b128 v[206:209], v170 offset:36864
	ds_read_b128 v[210:213], v170 offset:37888
	ds_read_b128 v[214:217], v170 offset:38912
	ds_read_b128 v[218:221], v170 offset:39936
	global_load_lds_dwordx4 v154, s[34:35]
	s_mov_b32 m0, s50
	s_nop 0
	global_load_lds_dwordx4 v156, s[34:35]
	s_waitcnt vmcnt(8)
	s_waitcnt lgkmcnt(0)
	s_barrier
	s_setprio 1
	s_waitcnt lgkmcnt(0)
	v_mfma_f32_16x16x32_bf16 v[122:125], v[126:129], v[180:183], v[122:125]
	v_mfma_f32_16x16x32_bf16 v[114:117], v[138:141], v[180:183], v[114:117]
	v_mfma_f32_16x16x32_bf16 v[106:109], v[126:129], v[198:201], v[106:109]
	v_mfma_f32_16x16x32_bf16 v[98:101], v[138:141], v[198:201], v[98:101]
	v_mfma_f32_16x16x32_bf16 v[90:93], v[126:129], v[206:209], v[90:93]
	v_mfma_f32_16x16x32_bf16 v[82:85], v[138:141], v[206:209], v[82:85]
	v_mfma_f32_16x16x32_bf16 v[74:77], v[126:129], v[214:217], v[74:77]
	v_mfma_f32_16x16x32_bf16 v[66:69], v[138:141], v[214:217], v[66:69]
	v_mfma_f32_16x16x32_bf16 v[122:125], v[134:137], v[184:187], v[122:125]
	v_mfma_f32_16x16x32_bf16 v[114:117], v[142:145], v[184:187], v[114:117]
	v_mfma_f32_16x16x32_bf16 v[106:109], v[134:137], v[202:205], v[106:109]
	v_mfma_f32_16x16x32_bf16 v[98:101], v[142:145], v[202:205], v[98:101]
	v_mfma_f32_16x16x32_bf16 v[90:93], v[134:137], v[210:213], v[90:93]
	v_mfma_f32_16x16x32_bf16 v[82:85], v[142:145], v[210:213], v[82:85]
	v_mfma_f32_16x16x32_bf16 v[74:77], v[134:137], v[218:221], v[74:77]
	v_mfma_f32_16x16x32_bf16 v[66:69], v[142:145], v[218:221], v[66:69]
	s_setprio 0
	s_setprio 1
	v_mfma_f32_16x16x32_bf16 v[130:133], v[146:149], v[180:183], v[130:133]
	v_mfma_f32_16x16x32_bf16 v[118:121], v[172:175], v[180:183], v[118:121]
	v_mfma_f32_16x16x32_bf16 v[110:113], v[146:149], v[198:201], v[110:113]
	v_mfma_f32_16x16x32_bf16 v[102:105], v[172:175], v[198:201], v[102:105]
	v_mfma_f32_16x16x32_bf16 v[94:97], v[146:149], v[206:209], v[94:97]
	v_mfma_f32_16x16x32_bf16 v[86:89], v[172:175], v[206:209], v[86:89]
	v_mfma_f32_16x16x32_bf16 v[78:81], v[146:149], v[214:217], v[78:81]
	v_mfma_f32_16x16x32_bf16 v[70:73], v[172:175], v[214:217], v[70:73]
	v_mfma_f32_16x16x32_bf16 v[130:133], v[150:153], v[184:187], v[130:133]
	v_mfma_f32_16x16x32_bf16 v[118:121], v[176:179], v[184:187], v[118:121]
	v_mfma_f32_16x16x32_bf16 v[110:113], v[150:153], v[202:205], v[110:113]
	v_mfma_f32_16x16x32_bf16 v[102:105], v[176:179], v[202:205], v[102:105]
	v_mfma_f32_16x16x32_bf16 v[94:97], v[150:153], v[210:213], v[94:97]
	v_mfma_f32_16x16x32_bf16 v[86:89], v[176:179], v[210:213], v[86:89]
	v_mfma_f32_16x16x32_bf16 v[78:81], v[150:153], v[218:221], v[78:81]
	v_mfma_f32_16x16x32_bf16 v[70:73], v[176:179], v[218:221], v[70:73]
	s_setprio 0
	s_barrier
	s_add_i32 s100, s55, s36
	s_add_u32 s28, s28, 0x80
	s_addc_u32 s29, s29, 0
	s_mov_b32 m0, s100
	ds_read_b128 v[180:183], v170 offset:49152
	ds_read_b128 v[184:187], v170 offset:50176
	ds_read_b128 v[198:201], v170 offset:51200
	ds_read_b128 v[202:205], v170 offset:52224
	ds_read_b128 v[206:209], v170 offset:53248
	ds_read_b128 v[210:213], v170 offset:54272
	ds_read_b128 v[214:217], v170 offset:55296
	ds_read_b128 v[218:221], v170 offset:56320
	global_load_lds_dwordx4 v48, s[28:29]
	s_add_i32 m0, s100, 0x2000
	s_add_u32 s68, s34, 0xfffc0080
	s_addc_u32 s69, s35, -1
	s_add_i32 s100, s56, s36
	global_load_lds_dwordx4 v158, s[28:29]
	s_add_u32 s28, s28, 0x40000
	s_addc_u32 s29, s29, 0
	s_mov_b32 m0, s100
	s_nop 0
	global_load_lds_dwordx4 v48, s[28:29]
	s_add_i32 m0, s100, 0x2000
	s_nop 0
	global_load_lds_dwordx4 v158, s[28:29]
	s_mov_b32 m0, s52
	s_nop 0
	global_load_lds_dwordx4 v154, s[68:69]
	s_mov_b32 m0, s53
	s_nop 0
	global_load_lds_dwordx4 v156, s[68:69]
	s_waitcnt vmcnt(8)
	s_waitcnt lgkmcnt(0)
	s_barrier
	s_setprio 1
	s_waitcnt lgkmcnt(0)
	v_mfma_f32_16x16x32_bf16 v[58:61], v[126:129], v[180:183], v[58:61]
	v_mfma_f32_16x16x32_bf16 v[50:53], v[138:141], v[180:183], v[50:53]
	v_mfma_f32_16x16x32_bf16 v[40:43], v[126:129], v[198:201], v[40:43]
	v_mfma_f32_16x16x32_bf16 v[32:35], v[138:141], v[198:201], v[32:35]
	v_mfma_f32_16x16x32_bf16 v[24:27], v[126:129], v[206:209], v[24:27]
	v_mfma_f32_16x16x32_bf16 v[16:19], v[138:141], v[206:209], v[16:19]
	v_mfma_f32_16x16x32_bf16 v[8:11], v[126:129], v[214:217], v[8:11]
	v_mfma_f32_16x16x32_bf16 v[0:3], v[138:141], v[214:217], v[0:3]
	v_mfma_f32_16x16x32_bf16 v[58:61], v[134:137], v[184:187], v[58:61]
	v_mfma_f32_16x16x32_bf16 v[50:53], v[142:145], v[184:187], v[50:53]
	v_mfma_f32_16x16x32_bf16 v[40:43], v[134:137], v[202:205], v[40:43]
	v_mfma_f32_16x16x32_bf16 v[32:35], v[142:145], v[202:205], v[32:35]
	v_mfma_f32_16x16x32_bf16 v[24:27], v[134:137], v[210:213], v[24:27]
	v_mfma_f32_16x16x32_bf16 v[16:19], v[142:145], v[210:213], v[16:19]
	v_mfma_f32_16x16x32_bf16 v[8:11], v[134:137], v[218:221], v[8:11]
	v_mfma_f32_16x16x32_bf16 v[0:3], v[142:145], v[218:221], v[0:3]
	s_setprio 0
	s_setprio 1
	v_mfma_f32_16x16x32_bf16 v[62:65], v[146:149], v[180:183], v[62:65]
	v_mfma_f32_16x16x32_bf16 v[54:57], v[172:175], v[180:183], v[54:57]
	v_mfma_f32_16x16x32_bf16 v[44:47], v[146:149], v[198:201], v[44:47]
	v_mfma_f32_16x16x32_bf16 v[36:39], v[172:175], v[198:201], v[36:39]
	v_mfma_f32_16x16x32_bf16 v[28:31], v[146:149], v[206:209], v[28:31]
	v_mfma_f32_16x16x32_bf16 v[20:23], v[172:175], v[206:209], v[20:23]
	v_mfma_f32_16x16x32_bf16 v[12:15], v[146:149], v[214:217], v[12:15]
	v_mfma_f32_16x16x32_bf16 v[4:7], v[172:175], v[214:217], v[4:7]
	v_mfma_f32_16x16x32_bf16 v[62:65], v[150:153], v[184:187], v[62:65]
	v_mfma_f32_16x16x32_bf16 v[54:57], v[176:179], v[184:187], v[54:57]
	v_mfma_f32_16x16x32_bf16 v[44:47], v[150:153], v[202:205], v[44:47]
	v_mfma_f32_16x16x32_bf16 v[36:39], v[176:179], v[202:205], v[36:39]
	v_mfma_f32_16x16x32_bf16 v[28:31], v[150:153], v[210:213], v[28:31]
	v_mfma_f32_16x16x32_bf16 v[20:23], v[176:179], v[210:213], v[20:23]
	v_mfma_f32_16x16x32_bf16 v[12:15], v[150:153], v[218:221], v[12:15]
	v_mfma_f32_16x16x32_bf16 v[4:7], v[176:179], v[218:221], v[4:7]
	s_setprio 0
	s_barrier
	s_add_i32 s54, s54, 2
	s_add_u32 s30, s30, 0x100
	s_addc_u32 s31, s31, 0
	s_add_u32 s45, s45, 0x100
	s_addc_u32 s46, s46, 0
	s_cmp_gt_u32 s54, 13
	s_cbranch_scc0 .LBB0_158
	s_and_b64 vcc, exec, s[18:19]
	s_cbranch_vccz .LBB0_161
	s_barrier
